# v52 plus attention pair loop: K-fragment LDS reads issued before the next pair's LDS-DMA block
# baseline (speedup 1.0000x reference)
; __device__ __forceinline__ void bias_tile_past(f32x16 (&s)[2], float nslope2, float negM0, float dt) {
;     const float slope2 = -nslope2;
; #pragma unroll
;     for (int sub = 0; sub < 2; ++sub) { const float cb = fmaf(nslope2, dt - 32.0f * (float)sub, negM0);
; #pragma unroll
;         for (int i = 0; i < 16; ++i) asm("v_fmamk_f32 %0, %1, %3, %2" : "=v"(s[sub][i]) : "v"(slope2), "v"(cb), "i"(__builtin_bit_cast(int, (float)((i & 3) + 8 * (i >> 2))))); }
; }
; template <bool PAST, bool PAST1 = PAST>
; __device__ __forceinline__ void attn_pair(f32x16 (&o)[4], float& lsum, const bf16x8 (&qf)[4], const LaneAddr& A, unsigned k0, unsigned v0, unsigned k1, unsigned v1, float nslope2, float negM0, float dt0, float dt1) {
;     bf16x8 kf[2][4];
;     f32x16 s0[2], s1[2];
;     bf16x8 pa0[2][2], pa1[2][2];
;     s16x4 vlo[2][4], vhi[2][4];
; #pragma unroll
;     for (int ks = 0; ks < 4; ++ks) { const unsigned ka = A.kb[ks] + k0; kf[0][ks] = *(const ALDS bf16x8*)(size_t)(ka); kf[1][ks] = *(const ALDS bf16x8*)(size_t)(ka + 8192u); }
;     if (PAST) bias_tile_past(s0, nslope2, negM0, dt0); else bias_tile(s0, nslope2, negM0, dt0);
; #pragma unroll
;     for (int ks = 0; ks < 4; ++ks) { MF32(s0[0], kf[0][ks], qf[ks]); MF32(s0[1], kf[1][ks], qf[ks]); }
;     SBAR0();
;     if (PAST1) bias_tile_past(s1, nslope2, negM0, dt1); else bias_tile(s1, nslope2, negM0, dt1);
;     unsigned va0[4][2];
; #pragma unroll
;     for (int et = 0; et < 4; ++et) { va0[et][0] = A.vb[2 * et] + v0; va0[et][1] = A.vb[2 * et + 1] + v0; }
;     bf16x8 k2[2][2];
;     { const unsigned ka = A.kb[0] + k1; k2[0][0] = *(const ALDS bf16x8*)(size_t)(ka); k2[0][1] = *(const ALDS bf16x8*)(size_t)(ka + 8192u); }
;     SBAR0();
; #pragma unroll
;     for (int g = 0; g < 8; ++g) {
;         const int ks = g >> 1, sub = g & 1;
;         if (sub == 0 && ks < 3) { const unsigned ka = A.kb[ks + 1] + k1; k2[(ks + 1) & 1][0] = *(const ALDS bf16x8*)(size_t)(ka); k2[(ks + 1) & 1][1] = *(const ALDS bf16x8*)(size_t)(ka + 8192u); }
;         MF32(s1[sub], k2[ks & 1][sub], qf[ks]);
; #pragma unroll
;         for (int k = 0; k < 4; ++k) { const int idx = 4 * g + k; s0[idx >> 4][idx & 15] = __builtin_amdgcn_exp2f(s0[idx >> 4][idx & 15]); lsum += s0[idx >> 4][idx & 15]; }
;         if (g & 1) pa0[g >> 2][(g >> 1) & 1] = pack8s(s0[g >> 2], 8 * ((g >> 1) & 1));
;         if (g == 6) {
; #pragma unroll
.LBB0_809:
	s_add_i32 s72, s24, 0xffff0000
	s_and_b32 s14, s72, 0x10000
	s_add_i32 s72, s14, 0
	v_add_u32_e32 v64, 64, v193
	v_cvt_f32_i32_e32 v68, v64
	v_add_u32_e32 v64, s72, v167
	ds_read_b128 v[70:73], v64
	ds_read_b128 v[64:67], v64 offset:8192
	v_add_u32_e32 v69, s72, v169
	ds_read_b128 v[214:217], v69
	ds_read_b128 v[74:77], v69 offset:8192
	v_add_u32_e32 v69, s72, v171
	ds_read_b128 v[218:221], v69
	ds_read_b128 v[78:81], v69 offset:8192
	v_add_u32_e32 v69, s72, v173
	ds_read_b128 v[222:225], v69
	ds_read_b128 v[82:85], v69 offset:8192
	s_and_b32 s14, s24, 0x10000
	s_add_i32 s73, s14, 0
	v_mad_u64_u32 v[248:249], s[14:15], s70, v211, v[144:145]
	s_add_i32 s14, s73, s84
	v_lshl_add_u64 v[250:251], v[248:249], 0, s[50:51]
	s_mov_b32 s15, m0
	s_mov_b32 m0, s14
	s_nop 0
	global_load_lds_dwordx4 v[250:251], off
	s_mov_b32 m0, s15
	v_lshl_add_u64 v[248:249], v[248:249], 0, s[52:53]
	s_add_i32 s14, s14, 0x8000
	s_mov_b32 s15, m0
	s_mov_b32 m0, s14
	s_nop 0
	global_load_lds_dwordx4 v[248:249], off
	s_mov_b32 m0, s15
	v_mad_u64_u32 v[248:249], s[14:15], s70, v211, v[146:147]
	s_add_i32 s14, s73, s85
	v_lshl_add_u64 v[250:251], v[248:249], 0, s[50:51]
	s_mov_b32 s15, m0
	s_mov_b32 m0, s14
	s_nop 0
	global_load_lds_dwordx4 v[250:251], off
	s_mov_b32 m0, s15
	v_lshl_add_u64 v[248:249], v[248:249], 0, s[52:53]
	s_add_i32 s14, s14, 0x8000
	s_mov_b32 s15, m0
	s_mov_b32 m0, s14
	s_nop 0
	global_load_lds_dwordx4 v[248:249], off
	s_mov_b32 m0, s15
	v_xor_b32_e32 v197, 0x80000000, v200
	v_mad_u64_u32 v[248:249], s[14:15], s70, v211, v[148:149]
	s_add_i32 s14, s73, s86
	v_lshl_add_u64 v[250:251], v[248:249], 0, s[50:51]
	s_mov_b32 s15, m0
	s_mov_b32 m0, s14
	s_nop 0
	global_load_lds_dwordx4 v[250:251], off
	s_mov_b32 m0, s15
	v_lshl_add_u64 v[248:249], v[248:249], 0, s[52:53]
	s_add_i32 s14, s14, 0x8000
	s_mov_b32 s15, m0
	s_mov_b32 m0, s14
	s_nop 0
	global_load_lds_dwordx4 v[248:249], off
	s_mov_b32 m0, s15
	s_nop 0
	v_mad_u64_u32 v[248:249], s[14:15], s70, v211, v[150:151]
	s_add_i32 s14, s73, s87
	v_lshl_add_u64 v[250:251], v[248:249], 0, s[50:51]
	s_mov_b32 s15, m0
	s_mov_b32 m0, s14
	s_nop 0
	global_load_lds_dwordx4 v[250:251], off
	s_mov_b32 m0, s15
	s_add_i32 s14, s14, 0x8000
	v_lshl_add_u64 v[248:249], v[248:249], 0, s[52:53]
	s_mov_b32 s15, m0
	s_mov_b32 m0, s14
	s_nop 0
	global_load_lds_dwordx4 v[248:249], off
	s_mov_b32 m0, s15
	v_fma_f32 v69, v200, v68, v174
	v_add_f32_e32 v68, 0xc2000000, v68
	v_fmamk_f32 v112, v197, 0, v69
	v_fmamk_f32 v113, v197, 0x3f800000, v69
	v_fmamk_f32 v114, v197, 0x40000000, v69
	v_fmamk_f32 v115, v197, 0x40400000, v69
	v_fmamk_f32 v116, v197, 0x41000000, v69
	v_fmamk_f32 v117, v197, 0x41100000, v69
	v_fmamk_f32 v118, v197, 0x41200000, v69
	v_fmamk_f32 v119, v197, 0x41300000, v69
	v_fmamk_f32 v120, v197, 0x41800000, v69
	v_fmamk_f32 v121, v197, 0x41880000, v69
	v_fmamk_f32 v122, v197, 0x41900000, v69
	v_fmamk_f32 v123, v197, 0x41980000, v69
	v_fmamk_f32 v124, v197, 0x41c00000, v69
	v_fmamk_f32 v125, v197, 0x41c80000, v69
	v_fmamk_f32 v126, v197, 0x41d00000, v69
	v_fmamk_f32 v127, v197, 0x41d80000, v69
	v_fma_f32 v68, v200, v68, v174
	v_fmamk_f32 v96, v197, 0, v68
	v_fmamk_f32 v97, v197, 0x3f800000, v68
	v_fmamk_f32 v98, v197, 0x40000000, v68
	v_fmamk_f32 v99, v197, 0x40400000, v68
	v_fmamk_f32 v100, v197, 0x41000000, v68
	v_fmamk_f32 v101, v197, 0x41100000, v68
	v_fmamk_f32 v102, v197, 0x41200000, v68
	v_fmamk_f32 v103, v197, 0x41300000, v68
	v_fmamk_f32 v104, v197, 0x41800000, v68
	v_fmamk_f32 v105, v197, 0x41880000, v68
	v_fmamk_f32 v106, v197, 0x41900000, v68
	v_fmamk_f32 v107, v197, 0x41980000, v68
	v_fmamk_f32 v108, v197, 0x41c00000, v68
	v_fmamk_f32 v109, v197, 0x41c80000, v68
	v_fmamk_f32 v110, v197, 0x41d00000, v68
	v_fmamk_f32 v111, v197, 0x41d80000, v68
	s_add_i32 s14, s72, 0x8000
	s_waitcnt lgkmcnt(6)
	v_mfma_f32_32x32x16_bf16 v[96:111], v[64:67], v[140:143], v[96:111]
	s_add_i32 s73, s72, 0x4000
	s_add_i32 s72, s72, 0xc000
	v_cvt_f32_i32_e32 v64, v193
	s_waitcnt lgkmcnt(4)
	v_mfma_f32_32x32x16_bf16 v[96:111], v[74:77], v[136:139], v[96:111]
	s_waitcnt lgkmcnt(2)
	v_mfma_f32_32x32x16_bf16 v[96:111], v[78:81], v[132:135], v[96:111]
	s_waitcnt lgkmcnt(0)
	v_mfma_f32_32x32x16_bf16 v[96:111], v[82:85], v[128:131], v[96:111]
	v_mfma_f32_32x32x16_bf16 v[112:127], v[70:73], v[140:143], v[112:127]
	v_fma_f32 v65, v200, v64, v174
	v_add_f32_e32 v64, 0xc2000000, v64
	v_fma_f32 v79, v200, v64, v174
	v_fmamk_f32 v80, v197, 0, v65
	v_fmamk_f32 v81, v197, 0x3f800000, v65
	v_fmamk_f32 v82, v197, 0x40000000, v65
	v_fmamk_f32 v83, v197, 0x40400000, v65
	v_mfma_f32_32x32x16_bf16 v[112:127], v[214:217], v[136:139], v[112:127]
	v_fmamk_f32 v84, v197, 0x41000000, v65
	v_fmamk_f32 v85, v197, 0x41100000, v65
	v_fmamk_f32 v86, v197, 0x41200000, v65
	v_fmamk_f32 v87, v197, 0x41300000, v65
	v_fmamk_f32 v88, v197, 0x41800000, v65
	v_fmamk_f32 v89, v197, 0x41880000, v65
	v_fmamk_f32 v90, v197, 0x41900000, v65
	v_mfma_f32_32x32x16_bf16 v[112:127], v[218:221], v[132:135], v[112:127]
	v_add_u32_e32 v219, s73, v167
	v_fmamk_f32 v91, v197, 0x41980000, v65
	v_fmamk_f32 v92, v197, 0x41c00000, v65
	v_fmamk_f32 v93, v197, 0x41c80000, v65
	v_fmamk_f32 v94, v197, 0x41d00000, v65
	v_fmamk_f32 v95, v197, 0x41d80000, v65
	v_fmamk_f32 v64, v197, 0, v79
	v_fmamk_f32 v65, v197, 0x3f800000, v79
	v_fmamk_f32 v66, v197, 0x40000000, v79
	v_fmamk_f32 v67, v197, 0x40400000, v79
	v_fmamk_f32 v68, v197, 0x41000000, v79
	v_fmamk_f32 v69, v197, 0x41100000, v79
	v_fmamk_f32 v70, v197, 0x41200000, v79
	v_fmamk_f32 v71, v197, 0x41300000, v79
	v_fmamk_f32 v72, v197, 0x41800000, v79
	v_fmamk_f32 v73, v197, 0x41880000, v79
	v_fmamk_f32 v74, v197, 0x41900000, v79
	v_fmamk_f32 v75, v197, 0x41980000, v79
	v_fmamk_f32 v76, v197, 0x41c00000, v79
	v_fmamk_f32 v77, v197, 0x41c80000, v79
	v_fmamk_f32 v78, v197, 0x41d00000, v79
	v_fmamk_f32 v79, v197, 0x41d80000, v79
	ds_read_b128 v[226:229], v219
	ds_read_b128 v[230:233], v219 offset:8192
	v_add_u32_e32 v197, s14, v159
	v_add_u32_e32 v199, s14, v202
	v_add_u32_e32 v213, s14, v161
	v_add_u32_e32 v214, s14, v203
	v_add_u32_e32 v215, s14, v163
	v_add_u32_e32 v216, s14, v204
	v_add_u32_e32 v217, s14, v165
	v_add_u32_e32 v218, s14, v205
	v_mfma_f32_32x32x16_bf16 v[112:127], v[222:225], v[128:131], v[112:127]
	s_nop 11
	v_exp_f32_e32 v112, v112
	v_exp_f32_e32 v113, v113
	v_add_u32_e32 v219, s73, v169
	v_exp_f32_e32 v114, v114
	ds_read_b128 v[220:223], v219
	ds_read_b128 v[234:237], v219 offset:8192
	v_exp_f32_e32 v115, v115
	v_add_f32_e32 v195, v195, v112
	v_add_f32_e32 v195, v113, v195
	v_add_f32_e32 v195, v114, v195
	v_add_f32_e32 v195, v115, v195
	s_waitcnt lgkmcnt(3)
; #define ALDS __attribute__((address_space(3)))
; #define SBAR0() __builtin_amdgcn_sched_barrier(0)
; template <bool PAST, bool PAST1 = PAST>
; __device__ __forceinline__ void attn_pair(f32x16 (&o)[4], float& lsum, const bf16x8 (&qf)[4], const LaneAddr& A, unsigned k0, unsigned v0, unsigned k1, unsigned v1, float nslope2, float negM0, float dt0, float dt1) {
;     ...
; #pragma unroll
;     for (int g = 0; g < 8; ++g) {
;         const int ks = g >> 1, sub = g & 1;
;         if (sub == 0 && ks < 3) { const unsigned ka = A.kb[ks + 1] + k1; k2[(ks + 1) & 1][0] = *(const ALDS bf16x8*)(size_t)(ka); k2[(ks + 1) & 1][1] = *(const ALDS bf16x8*)(size_t)(ka + 8192u); }
;         MF32(s1[sub], k2[ks & 1][sub], qf[ks]);
; #pragma unroll
;         for (int k = 0; k < 4; ++k) { const int idx = 4 * g + k; s0[idx >> 4][idx & 15] = __builtin_amdgcn_exp2f(s0[idx >> 4][idx & 15]); lsum += s0[idx >> 4][idx & 15]; }
;         if (g & 1) pa0[g >> 2][(g >> 1) & 1] = pack8s(s0[g >> 2], 8 * ((g >> 1) & 1));
;         if (g == 6) {
; #pragma unroll
;             for (int et = 0; et < 4; ++et) { TR_ISSUE(vlo[0][et], va0[et][0], 0); TR_ISSUE(vhi[0][et], va0[et][1], 2048); } }
;         SBAR0();
;     }
;     tr_wait<4>(vlo[0], vhi[0]);
;     SBAR0();
;     unsigned va1[4][2];
; #pragma unroll
;     for (int g = 0; g < 16; ++g) {
;         const int step = g >> 2, et = g & 3, cur = step & 1, nxt = cur ^ 1;
;         if (et == 0) {
;             if (step < 3) {
; #pragma unroll
;                 for (int e2 = 0; e2 < 4; ++e2) { TR_ISSUE(vlo[nxt][e2], va0[e2][0], 256 * (32 * ((step + 1) >> 1) + 16 * ((step + 1) & 1))); TR_ISSUE(vhi[nxt][e2], va0[e2][1], 256 * (32 * ((step + 1) >> 1) + 16 * ((step + 1) & 1)) + 2048); }
;             } else {
; #pragma unroll
;                 for (int e2 = 0; e2 < 4; ++e2) { va1[e2][0] = A.vb[2 * e2] + v1; va1[e2][1] = A.vb[2 * e2 + 1] + v1; TR_ISSUE(vlo[nxt][e2], va1[e2][0], 0); TR_ISSUE(vhi[nxt][e2], va1[e2][1], 2048); }
;             }
;         }
;         MF32(o[et], VFRAG(cur, et), pa0[step >> 1][step & 1]);
; #pragma unroll
;         for (int k = 0; k < 2; ++k) { const int idx = 2 * g + k; s1[idx >> 4][idx & 15] = __builtin_amdgcn_exp2f(s1[idx >> 4][idx & 15]); lsum += s1[idx >> 4][idx & 15]; }
;         if (et == 3) { pa1[step >> 1][step & 1] = pack8s(s1[step >> 1], 8 * (step & 1)); tr_wait<4>(vlo[nxt], vhi[nxt]); }
;         SBAR0();
;     }
	v_mfma_f32_32x32x16_bf16 v[80:95], v[226:229], v[140:143], v[80:95]
	v_exp_f32_e32 v219, v116
	v_exp_f32_e32 v224, v118
	v_exp_f32_e32 v119, v119
	s_waitcnt lgkmcnt(2)
	v_mfma_f32_32x32x16_bf16 v[64:79], v[230:233], v[140:143], v[64:79]
	v_add_f32_e32 v116, v219, v195
	v_exp_f32_e32 v195, v117
	v_cvt_pk_bf16_f32 v117, v114, v115
	v_add_f32_e32 v116, v195, v116
	v_add_f32_e32 v116, v224, v116
	v_add_f32_e32 v232, v119, v116
	v_cvt_pk_bf16_f32 v116, v112, v113
	v_cvt_pk_bf16_f32 v118, v219, v195
	v_cvt_pk_bf16_f32 v119, v224, v119
	v_add_u32_e32 v112, s73, v171
	ds_read_b128 v[224:227], v112
	ds_read_b128 v[228:231], v112 offset:8192
	v_exp_f32_e32 v112, v120
	v_exp_f32_e32 v113, v121
	v_exp_f32_e32 v114, v122
	v_exp_f32_e32 v115, v123
	v_add_f32_e32 v120, v112, v232
	v_add_f32_e32 v120, v113, v120
	v_add_f32_e32 v120, v114, v120
	s_waitcnt lgkmcnt(3)
	v_mfma_f32_32x32x16_bf16 v[80:95], v[220:223], v[136:139], v[80:95]
	v_add_f32_e32 v120, v115, v120
	v_exp_f32_e32 v121, v124
	v_exp_f32_e32 v122, v125
	v_exp_f32_e32 v123, v126
	v_exp_f32_e32 v124, v127
	v_add_f32_e32 v120, v121, v120
	v_add_f32_e32 v120, v122, v120
	v_add_f32_e32 v120, v123, v120
	v_add_f32_e32 v195, v124, v120
	s_waitcnt lgkmcnt(2)
	v_mfma_f32_32x32x16_bf16 v[64:79], v[234:237], v[136:139], v[64:79]
	v_cvt_pk_bf16_f32 v112, v112, v113
	v_cvt_pk_bf16_f32 v113, v114, v115
	v_cvt_pk_bf16_f32 v114, v121, v122
	v_cvt_pk_bf16_f32 v115, v123, v124
	v_exp_f32_e32 v96, v96
	v_exp_f32_e32 v97, v97
	v_add_u32_e32 v124, s73, v173
	v_exp_f32_e32 v98, v98
	ds_read_b128 v[120:123], v124
	ds_read_b128 v[124:127], v124 offset:8192
	v_exp_f32_e32 v99, v99
	v_add_f32_e32 v195, v96, v195
	v_add_f32_e32 v195, v97, v195
	v_add_f32_e32 v195, v98, v195
	v_add_f32_e32 v195, v99, v195
	s_waitcnt lgkmcnt(3)
	v_mfma_f32_32x32x16_bf16 v[80:95], v[224:227], v[132:135], v[80:95]
	v_exp_f32_e32 v219, v100
	v_exp_f32_e32 v220, v102
	v_exp_f32_e32 v103, v103
	s_waitcnt lgkmcnt(2)
	v_mfma_f32_32x32x16_bf16 v[64:79], v[228:231], v[132:135], v[64:79]
	v_add_f32_e32 v100, v219, v195
	v_exp_f32_e32 v195, v101
	v_cvt_pk_bf16_f32 v101, v98, v99
	v_add_f32_e32 v100, v195, v100
	v_add_f32_e32 v100, v220, v100
	v_add_f32_e32 v221, v103, v100
	v_cvt_pk_bf16_f32 v100, v96, v97
	v_cvt_pk_bf16_f32 v102, v219, v195
	v_cvt_pk_bf16_f32 v103, v220, v103
	v_exp_f32_e32 v96, v104
	s_waitcnt lgkmcnt(1)
	v_mfma_f32_32x32x16_bf16 v[80:95], v[120:123], v[128:131], v[80:95]
	v_exp_f32_e32 v98, v105
	v_exp_f32_e32 v99, v106
	v_add_f32_e32 v97, v96, v221
	v_exp_f32_e32 v195, v107
	ds_read_b64_tr_b16 v[104:105], v197
	ds_read_b64_tr_b16 v[106:107], v199 offset:2048
	ds_read_b64_tr_b16 v[120:121], v213
	ds_read_b64_tr_b16 v[122:123], v214 offset:2048
	ds_read_b64_tr_b16 v[220:221], v215
	ds_read_b64_tr_b16 v[222:223], v216 offset:2048
	ds_read_b64_tr_b16 v[224:225], v217
	ds_read_b64_tr_b16 v[226:227], v218 offset:2048
	v_add_f32_e32 v97, v98, v97
	v_add_f32_e32 v97, v99, v97
	v_add_f32_e32 v97, v195, v97
	v_exp_f32_e32 v108, v108
	v_exp_f32_e32 v109, v109
	v_exp_f32_e32 v110, v110
	v_exp_f32_e32 v111, v111
	v_add_f32_e32 v97, v108, v97
	v_add_f32_e32 v97, v109, v97
	v_add_f32_e32 v97, v110, v97
	s_waitcnt lgkmcnt(8)
	v_mfma_f32_32x32x16_bf16 v[64:79], v[124:127], v[128:131], v[64:79]
	v_add_f32_e32 v219, v111, v97
	v_cvt_pk_bf16_f32 v96, v96, v98
	v_cvt_pk_bf16_f32 v97, v99, v195
	v_cvt_pk_bf16_f32 v98, v108, v109
	v_cvt_pk_bf16_f32 v99, v110, v111
	ds_read_b64_tr_b16 v[108:109], v197 offset:4096
	ds_read_b64_tr_b16 v[110:111], v199 offset:6144
	ds_read_b64_tr_b16 v[124:125], v213 offset:4096
	ds_read_b64_tr_b16 v[126:127], v214 offset:6144
	ds_read_b64_tr_b16 v[228:229], v215 offset:4096
	ds_read_b64_tr_b16 v[230:231], v216 offset:6144
	ds_read_b64_tr_b16 v[232:233], v217 offset:4096
	ds_read_b64_tr_b16 v[234:235], v218 offset:6144
	s_waitcnt lgkmcnt(14)
	v_mfma_f32_32x32x16_bf16 v[48:63], v[104:107], v[116:119], v[48:63]
	v_exp_f32_e32 v80, v80
	v_exp_f32_e32 v81, v81
	v_add_f32_e32 v104, v80, v219
	v_add_f32_e32 v104, v81, v104
	s_waitcnt lgkmcnt(12)
	v_mfma_f32_32x32x16_bf16 v[32:47], v[120:123], v[116:119], v[32:47]
	v_exp_f32_e32 v82, v82
	v_exp_f32_e32 v83, v83
	v_add_f32_e32 v104, v82, v104
	v_add_f32_e32 v104, v83, v104
	s_waitcnt lgkmcnt(10)
	v_mfma_f32_32x32x16_bf16 v[16:31], v[220:223], v[116:119], v[16:31]
	v_exp_f32_e32 v84, v84
	v_exp_f32_e32 v85, v85
	v_add_f32_e32 v104, v84, v104
	v_add_f32_e32 v104, v85, v104
	s_waitcnt lgkmcnt(8)
	v_mfma_f32_32x32x16_bf16 v[0:15], v[224:227], v[116:119], v[0:15]
	v_exp_f32_e32 v86, v86
	v_exp_f32_e32 v87, v87
	v_cvt_pk_bf16_f32 v80, v80, v81
	v_cvt_pk_bf16_f32 v81, v82, v83
	v_add_f32_e32 v104, v86, v104
	v_add_f32_e32 v195, v87, v104
	v_cvt_pk_bf16_f32 v82, v84, v85
	v_cvt_pk_bf16_f32 v83, v86, v87
	ds_read_b64_tr_b16 v[104:105], v197 offset:8192
	ds_read_b64_tr_b16 v[106:107], v199 offset:10240
	ds_read_b64_tr_b16 v[116:117], v213 offset:8192
	ds_read_b64_tr_b16 v[118:119], v214 offset:10240
	ds_read_b64_tr_b16 v[120:121], v215 offset:8192
	ds_read_b64_tr_b16 v[122:123], v216 offset:10240
	ds_read_b64_tr_b16 v[220:221], v217 offset:8192
	ds_read_b64_tr_b16 v[222:223], v218 offset:10240
	s_waitcnt lgkmcnt(14)
	v_mfma_f32_32x32x16_bf16 v[48:63], v[108:111], v[112:115], v[48:63]
	v_exp_f32_e32 v84, v88
	v_exp_f32_e32 v86, v89
	v_add_f32_e32 v85, v84, v195
	v_add_f32_e32 v85, v86, v85
	s_waitcnt lgkmcnt(12)
	v_mfma_f32_32x32x16_bf16 v[32:47], v[124:127], v[112:115], v[32:47]
	v_exp_f32_e32 v87, v90
	v_exp_f32_e32 v88, v91
	v_add_f32_e32 v85, v87, v85
	v_add_f32_e32 v85, v88, v85
	s_waitcnt lgkmcnt(10)
; template <bool PAST, bool PAST1 = PAST>
; __device__ __forceinline__ void attn_pair(f32x16 (&o)[4], float& lsum, const bf16x8 (&qf)[4], const LaneAddr& A, unsigned k0, unsigned v0, unsigned k1, unsigned v1, float nslope2, float negM0, float dt0, float dt1) {
;     ...
;     unsigned va1[4][2];
; #pragma unroll
;     for (int g = 0; g < 16; ++g) {
;         const int step = g >> 2, et = g & 3, cur = step & 1, nxt = cur ^ 1;
;         if (et == 0) {
;             if (step < 3) {
; #pragma unroll
;                 for (int e2 = 0; e2 < 4; ++e2) { TR_ISSUE(vlo[nxt][e2], va0[e2][0], 256 * (32 * ((step + 1) >> 1) + 16 * ((step + 1) & 1))); TR_ISSUE(vhi[nxt][e2], va0[e2][1], 256 * (32 * ((step + 1) >> 1) + 16 * ((step + 1) & 1)) + 2048); }
;             } else {
; #pragma unroll
;                 for (int e2 = 0; e2 < 4; ++e2) { va1[e2][0] = A.vb[2 * e2] + v1; va1[e2][1] = A.vb[2 * e2 + 1] + v1; TR_ISSUE(vlo[nxt][e2], va1[e2][0], 0); TR_ISSUE(vhi[nxt][e2], va1[e2][1], 2048); }
;             }
;         }
;         MF32(o[et], VFRAG(cur, et), pa0[step >> 1][step & 1]);
; #pragma unroll
;         for (int k = 0; k < 2; ++k) { const int idx = 2 * g + k; s1[idx >> 4][idx & 15] = __builtin_amdgcn_exp2f(s1[idx >> 4][idx & 15]); lsum += s1[idx >> 4][idx & 15]; }
;         if (et == 3) { pa1[step >> 1][step & 1] = pack8s(s1[step >> 1], 8 * (step & 1)); tr_wait<4>(vlo[nxt], vhi[nxt]); }
;         SBAR0();
;     }
;     if (PROBE == 7) { float dmy = negM0;
; #pragma unroll
;         for (int i = 0; i < 64; ++i) asm volatile("v_exp_f32 %0, %0" : "+v"(dmy)); }
;     if (PROBE == 8) { s16x4 dm;
; #pragma unroll
;         for (int i = 0; i < 64; ++i) asm volatile("ds_read_b64_tr_b16 %0, %1 offset:%c2" : "=&v"(dm) : "v"(va1[i & 3][0]), "i"((i >> 2) * 512) : "memory");
;         asm volatile("s_waitcnt lgkmcnt(0)" ::: "memory"); }
; #pragma unroll
;     for (int step = 0; step < 4; ++step) {
;         const int cur = step & 1, nxt = cur ^ 1;
;         if (step < 3) {
; #pragma unroll
;             for (int e2 = 0; e2 < 4; ++e2) { TR_ISSUE(vlo[nxt][e2], va1[e2][0], 256 * (32 * ((step + 1) >> 1) + 16 * ((step + 1) & 1))); TR_ISSUE(vhi[nxt][e2], va1[e2][1], 256 * (32 * ((step + 1) >> 1) + 16 * ((step + 1) & 1)) + 2048); } }
; #pragma unroll
;         for (int et = 0; et < 4; ++et) MF32(o[et], VFRAG(cur, et), pa1[step >> 1][step & 1]);
;         if (step < 3) tr_wait<4>(vlo[nxt], vhi[nxt]);
	v_mfma_f32_32x32x16_bf16 v[16:31], v[228:231], v[112:115], v[16:31]
	v_exp_f32_e32 v89, v92
	v_exp_f32_e32 v90, v93
	v_add_f32_e32 v85, v89, v85
	v_add_f32_e32 v85, v90, v85
	s_waitcnt lgkmcnt(8)
	v_mfma_f32_32x32x16_bf16 v[0:15], v[232:235], v[112:115], v[0:15]
	v_exp_f32_e32 v91, v94
	v_exp_f32_e32 v92, v95
	v_cvt_pk_bf16_f32 v84, v84, v86
	v_cvt_pk_bf16_f32 v86, v89, v90
	v_add_f32_e32 v85, v91, v85
	v_add_f32_e32 v124, v92, v85
	v_cvt_pk_bf16_f32 v85, v87, v88
	v_cvt_pk_bf16_f32 v87, v91, v92
	ds_read_b64_tr_b16 v[88:89], v197 offset:12288
	ds_read_b64_tr_b16 v[90:91], v199 offset:14336
	ds_read_b64_tr_b16 v[92:93], v213 offset:12288
	ds_read_b64_tr_b16 v[94:95], v214 offset:14336
	ds_read_b64_tr_b16 v[108:109], v215 offset:12288
	ds_read_b64_tr_b16 v[110:111], v216 offset:14336
	ds_read_b64_tr_b16 v[112:113], v217 offset:12288
	ds_read_b64_tr_b16 v[114:115], v218 offset:14336
	s_waitcnt lgkmcnt(14)
	v_mfma_f32_32x32x16_bf16 v[48:63], v[104:107], v[100:103], v[48:63]
	v_exp_f32_e32 v64, v64
	v_exp_f32_e32 v65, v65
	v_add_f32_e32 v104, v64, v124
	v_add_f32_e32 v104, v65, v104
	s_waitcnt lgkmcnt(12)
	v_mfma_f32_32x32x16_bf16 v[32:47], v[116:119], v[100:103], v[32:47]
	v_exp_f32_e32 v66, v66
	v_exp_f32_e32 v67, v67
	v_add_f32_e32 v104, v66, v104
	v_add_f32_e32 v104, v67, v104
	s_waitcnt lgkmcnt(10)
	v_mfma_f32_32x32x16_bf16 v[16:31], v[120:123], v[100:103], v[16:31]
	v_exp_f32_e32 v68, v68
	v_exp_f32_e32 v69, v69
	v_add_f32_e32 v104, v68, v104
	v_add_f32_e32 v104, v69, v104
	s_waitcnt lgkmcnt(8)
	v_mfma_f32_32x32x16_bf16 v[0:15], v[220:223], v[100:103], v[0:15]
	v_exp_f32_e32 v70, v70
	v_exp_f32_e32 v71, v71
	v_cvt_pk_bf16_f32 v64, v64, v65
	v_cvt_pk_bf16_f32 v65, v66, v67
	v_add_f32_e32 v100, v70, v104
	v_add_f32_e32 v120, v71, v100
	v_cvt_pk_bf16_f32 v66, v68, v69
	v_cvt_pk_bf16_f32 v67, v70, v71
	s_waitcnt lgkmcnt(6)
	v_mfma_f32_32x32x16_bf16 v[48:63], v[88:91], v[96:99], v[48:63]
	v_exp_f32_e32 v199, v72
	v_add_u32_e32 v121, s72, v159
	v_add_u32_e32 v123, s72, v161
	v_add_u32_e32 v125, s72, v163
	v_add_u32_e32 v127, s72, v165
	v_add_u32_e32 v122, s72, v202
	ds_read_b64_tr_b16 v[68:69], v121
	ds_read_b64_tr_b16 v[70:71], v122 offset:2048
	v_add_u32_e32 v124, s72, v203
	ds_read_b64_tr_b16 v[100:101], v123
	ds_read_b64_tr_b16 v[102:103], v124 offset:2048
	v_add_u32_e32 v126, s72, v204
	ds_read_b64_tr_b16 v[104:105], v125
	ds_read_b64_tr_b16 v[106:107], v126 offset:2048
	v_add_u32_e32 v197, s72, v205
	ds_read_b64_tr_b16 v[116:117], v127
	ds_read_b64_tr_b16 v[118:119], v197 offset:2048
	v_add_f32_e32 v72, v199, v120
	v_exp_f32_e32 v120, v73
	s_nop 0
	v_add_f32_e32 v72, v120, v72
	s_waitcnt lgkmcnt(12)
	v_mfma_f32_32x32x16_bf16 v[32:47], v[92:95], v[96:99], v[32:47]
	v_exp_f32_e32 v92, v74
	v_exp_f32_e32 v93, v75
	v_add_f32_e32 v72, v92, v72
	v_add_f32_e32 v72, v93, v72
	s_waitcnt lgkmcnt(10)
	v_mfma_f32_32x32x16_bf16 v[16:31], v[108:111], v[96:99], v[16:31]
	v_exp_f32_e32 v94, v76
	v_exp_f32_e32 v95, v77
	v_add_f32_e32 v72, v94, v72
	v_add_f32_e32 v72, v95, v72
	s_waitcnt lgkmcnt(8)
	v_mfma_f32_32x32x16_bf16 v[0:15], v[112:115], v[96:99], v[0:15]
	v_exp_f32_e32 v96, v78
	v_exp_f32_e32 v97, v79
	v_add_f32_e32 v72, v96, v72
	v_add_f32_e32 v195, v97, v72
	s_waitcnt lgkmcnt(6)
	v_mfma_f32_32x32x16_bf16 v[48:63], v[68:71], v[80:83], v[48:63]
	ds_read_b64_tr_b16 v[68:69], v121 offset:4096
	ds_read_b64_tr_b16 v[70:71], v122 offset:6144
	ds_read_b64_tr_b16 v[72:73], v123 offset:4096
	ds_read_b64_tr_b16 v[74:75], v124 offset:6144
	ds_read_b64_tr_b16 v[76:77], v125 offset:4096
	ds_read_b64_tr_b16 v[78:79], v126 offset:6144
	ds_read_b64_tr_b16 v[88:89], v127 offset:4096
	ds_read_b64_tr_b16 v[90:91], v197 offset:6144
	s_waitcnt lgkmcnt(12)
	v_mfma_f32_32x32x16_bf16 v[32:47], v[100:103], v[80:83], v[32:47]
	s_waitcnt lgkmcnt(10)
	v_mfma_f32_32x32x16_bf16 v[16:31], v[104:107], v[80:83], v[16:31]
	s_waitcnt lgkmcnt(8)
	v_mfma_f32_32x32x16_bf16 v[0:15], v[116:119], v[80:83], v[0:15]
	s_waitcnt lgkmcnt(6)
	v_mfma_f32_32x32x16_bf16 v[48:63], v[68:71], v[84:87], v[48:63]
	ds_read_b64_tr_b16 v[68:69], v121 offset:8192
	s_waitcnt lgkmcnt(5)
	v_mfma_f32_32x32x16_bf16 v[32:47], v[72:75], v[84:87], v[32:47]
	s_waitcnt lgkmcnt(3)
	v_mfma_f32_32x32x16_bf16 v[16:31], v[76:79], v[84:87], v[16:31]
	ds_read_b64_tr_b16 v[70:71], v122 offset:10240
	ds_read_b64_tr_b16 v[72:73], v123 offset:8192
	ds_read_b64_tr_b16 v[74:75], v124 offset:10240
	ds_read_b64_tr_b16 v[76:77], v125 offset:8192
	ds_read_b64_tr_b16 v[78:79], v126 offset:10240
	ds_read_b64_tr_b16 v[80:81], v127 offset:8192
	ds_read_b64_tr_b16 v[82:83], v197 offset:10240
	s_waitcnt lgkmcnt(8)
	v_mfma_f32_32x32x16_bf16 v[0:15], v[88:91], v[84:87], v[0:15]
	s_waitcnt lgkmcnt(6)
	v_mfma_f32_32x32x16_bf16 v[48:63], v[68:71], v[64:67], v[48:63]
	ds_read_b64_tr_b16 v[68:69], v121 offset:12288
	s_waitcnt lgkmcnt(5)
	v_mfma_f32_32x32x16_bf16 v[32:47], v[72:75], v[64:67], v[32:47]
	s_waitcnt lgkmcnt(3)
	v_mfma_f32_32x32x16_bf16 v[16:31], v[76:79], v[64:67], v[16:31]
	ds_read_b64_tr_b16 v[70:71], v122 offset:14336
	ds_read_b64_tr_b16 v[72:73], v123 offset:12288
	ds_read_b64_tr_b16 v[74:75], v124 offset:14336
	ds_read_b64_tr_b16 v[76:77], v125 offset:12288
	ds_read_b64_tr_b16 v[78:79], v126 offset:14336
	ds_read_b64_tr_b16 v[84:85], v127 offset:12288
	ds_read_b64_tr_b16 v[86:87], v197 offset:14336
	s_waitcnt lgkmcnt(8)
	v_mfma_f32_32x32x16_bf16 v[0:15], v[80:83], v[64:67], v[0:15]
	v_cvt_pk_bf16_f32 v64, v199, v120
	v_cvt_pk_bf16_f32 v65, v92, v93
	v_cvt_pk_bf16_f32 v66, v94, v95
	v_cvt_pk_bf16_f32 v67, v96, v97
	s_waitcnt lgkmcnt(6)
	s_nop 0
	v_mfma_f32_32x32x16_bf16 v[48:63], v[68:71], v[64:67], v[48:63]
	s_waitcnt lgkmcnt(4)
	v_mfma_f32_32x32x16_bf16 v[32:47], v[72:75], v[64:67], v[32:47]
	s_waitcnt lgkmcnt(2)
	v_mfma_f32_32x32x16_bf16 v[16:31], v[76:79], v[64:67], v[16:31]
	s_waitcnt lgkmcnt(0)
	v_mfma_f32_32x32x16_bf16 v[0:15], v[84:87], v[64:67], v[0:15]
	s_waitcnt vmcnt(0) lgkmcnt(0)
	s_barrier
	s_add_i32 s71, s71, -1
	s_add_i32 s24, s24, 0x10000
	s_addk_i32 s70, 0x80
	s_cmp_eq_u32 s71, 0
	v_add_u32_e32 v193, 0xffffff80, v193
	s_cbranch_scc0 .LBB0_809

; __device__ __forceinline__ void bias_tile_past(f32x16 (&s)[2], float nslope2, float negM0, float dt) {
;     const float slope2 = -nslope2;
; #pragma unroll
;     for (int sub = 0; sub < 2; ++sub) { const float cb = fmaf(nslope2, dt - 32.0f * (float)sub, negM0);
; #pragma unroll
;         for (int i = 0; i < 16; ++i) asm("v_fmamk_f32 %0, %1, %3, %2" : "=v"(s[sub][i]) : "v"(slope2), "v"(cb), "i"(__builtin_bit_cast(int, (float)((i & 3) + 8 * (i >> 2))))); }
; }
; template <bool PAST, bool PAST1 = PAST>
; __device__ __forceinline__ void attn_pair(f32x16 (&o)[4], float& lsum, const bf16x8 (&qf)[4], const LaneAddr& A, unsigned k0, unsigned v0, unsigned k1, unsigned v1, float nslope2, float negM0, float dt0, float dt1) {
;     bf16x8 kf[2][4];
;     f32x16 s0[2], s1[2];
;     bf16x8 pa0[2][2], pa1[2][2];
;     s16x4 vlo[2][4], vhi[2][4];
; #pragma unroll
;     for (int ks = 0; ks < 4; ++ks) { const unsigned ka = A.kb[ks] + k0; kf[0][ks] = *(const ALDS bf16x8*)(size_t)(ka); kf[1][ks] = *(const ALDS bf16x8*)(size_t)(ka + 8192u); }
;     if (PAST) bias_tile_past(s0, nslope2, negM0, dt0); else bias_tile(s0, nslope2, negM0, dt0);
; #pragma unroll
;     for (int ks = 0; ks < 4; ++ks) { MF32(s0[0], kf[0][ks], qf[ks]); MF32(s0[1], kf[1][ks], qf[ks]); }
;     SBAR0();
;     if (PAST1) bias_tile_past(s1, nslope2, negM0, dt1); else bias_tile(s1, nslope2, negM0, dt1);
;     unsigned va0[4][2];
; #pragma unroll
;     for (int et = 0; et < 4; ++et) { va0[et][0] = A.vb[2 * et] + v0; va0[et][1] = A.vb[2 * et + 1] + v0; }
;     bf16x8 k2[2][2];
;     { const unsigned ka = A.kb[0] + k1; k2[0][0] = *(const ALDS bf16x8*)(size_t)(ka); k2[0][1] = *(const ALDS bf16x8*)(size_t)(ka + 8192u); }
;     SBAR0();
; #pragma unroll
;     for (int g = 0; g < 8; ++g) {
;         const int ks = g >> 1, sub = g & 1;
;         if (sub == 0 && ks < 3) { const unsigned ka = A.kb[ks + 1] + k1; k2[(ks + 1) & 1][0] = *(const ALDS bf16x8*)(size_t)(ka); k2[(ks + 1) & 1][1] = *(const ALDS bf16x8*)(size_t)(ka + 8192u); }
;         MF32(s1[sub], k2[ks & 1][sub], qf[ks]);
; #pragma unroll
;         for (int k = 0; k < 4; ++k) { const int idx = 4 * g + k; s0[idx >> 4][idx & 15] = __builtin_amdgcn_exp2f(s0[idx >> 4][idx & 15]); lsum += s0[idx >> 4][idx & 15]; }
;         if (g & 1) pa0[g >> 2][(g >> 1) & 1] = pack8s(s0[g >> 2], 8 * ((g >> 1) & 1));
;         if (g == 6) {
; #pragma unroll
.LBB0_1853:
	s_add_i32 s66, s22, 0xffff0000
	s_and_b32 s4, s66, 0x10000
	s_add_i32 s66, s4, 0
	v_add_u32_e32 v64, 64, v193
	v_cvt_f32_i32_e32 v68, v64
	v_add_u32_e32 v64, s66, v167
	ds_read_b128 v[70:73], v64
	ds_read_b128 v[64:67], v64 offset:8192
	v_add_u32_e32 v69, s66, v169
	ds_read_b128 v[214:217], v69
	ds_read_b128 v[74:77], v69 offset:8192
	v_add_u32_e32 v69, s66, v171
	ds_read_b128 v[218:221], v69
	ds_read_b128 v[78:81], v69 offset:8192
	v_add_u32_e32 v69, s66, v173
	ds_read_b128 v[222:225], v69
	ds_read_b128 v[82:85], v69 offset:8192
	s_and_b32 s4, s22, 0x10000
	s_add_i32 s67, s4, 0
	v_mad_u64_u32 v[248:249], s[4:5], s64, v211, v[144:145]
	s_add_i32 s4, s67, s84
	v_lshl_add_u64 v[250:251], v[248:249], 0, s[40:41]
	s_mov_b32 s5, m0
	s_mov_b32 m0, s4
	s_nop 0
	global_load_lds_dwordx4 v[250:251], off
	s_mov_b32 m0, s5
	v_lshl_add_u64 v[248:249], v[248:249], 0, s[46:47]
	s_add_i32 s4, s4, 0x8000
	s_mov_b32 s5, m0
	s_mov_b32 m0, s4
	s_nop 0
	global_load_lds_dwordx4 v[248:249], off
	s_mov_b32 m0, s5
	v_mad_u64_u32 v[248:249], s[4:5], s64, v211, v[146:147]
	s_add_i32 s4, s67, s85
	v_lshl_add_u64 v[250:251], v[248:249], 0, s[40:41]
	s_mov_b32 s5, m0
	s_mov_b32 m0, s4
	s_nop 0
	global_load_lds_dwordx4 v[250:251], off
	s_mov_b32 m0, s5
	v_lshl_add_u64 v[248:249], v[248:249], 0, s[46:47]
	s_add_i32 s4, s4, 0x8000
	s_mov_b32 s5, m0
	s_mov_b32 m0, s4
	s_nop 0
	global_load_lds_dwordx4 v[248:249], off
	s_mov_b32 m0, s5
	v_xor_b32_e32 v197, 0x80000000, v200
	v_mad_u64_u32 v[248:249], s[4:5], s64, v211, v[148:149]
	s_add_i32 s4, s67, s86
	v_lshl_add_u64 v[250:251], v[248:249], 0, s[40:41]
	s_mov_b32 s5, m0
	s_mov_b32 m0, s4
	s_nop 0
	global_load_lds_dwordx4 v[250:251], off
	s_mov_b32 m0, s5
	v_lshl_add_u64 v[248:249], v[248:249], 0, s[46:47]
	s_add_i32 s4, s4, 0x8000
	s_mov_b32 s5, m0
	s_mov_b32 m0, s4
	s_nop 0
	global_load_lds_dwordx4 v[248:249], off
	s_mov_b32 m0, s5
	s_nop 0
	v_mad_u64_u32 v[248:249], s[4:5], s64, v211, v[150:151]
	s_add_i32 s4, s67, s87
	v_lshl_add_u64 v[250:251], v[248:249], 0, s[40:41]
	s_mov_b32 s5, m0
	s_mov_b32 m0, s4
	s_nop 0
	global_load_lds_dwordx4 v[250:251], off
	s_mov_b32 m0, s5
	s_add_i32 s4, s4, 0x8000
	v_lshl_add_u64 v[248:249], v[248:249], 0, s[46:47]
	s_mov_b32 s5, m0
	s_mov_b32 m0, s4
	s_nop 0
	global_load_lds_dwordx4 v[248:249], off
	s_mov_b32 m0, s5
	v_fma_f32 v69, v200, v68, v174
	v_add_f32_e32 v68, 0xc2000000, v68
	v_fmamk_f32 v112, v197, 0, v69
	v_fmamk_f32 v113, v197, 0x3f800000, v69
	v_fmamk_f32 v114, v197, 0x40000000, v69
	v_fmamk_f32 v115, v197, 0x40400000, v69
	v_fmamk_f32 v116, v197, 0x41000000, v69
	v_fmamk_f32 v117, v197, 0x41100000, v69
	v_fmamk_f32 v118, v197, 0x41200000, v69
	v_fmamk_f32 v119, v197, 0x41300000, v69
	v_fmamk_f32 v120, v197, 0x41800000, v69
	v_fmamk_f32 v121, v197, 0x41880000, v69
	v_fmamk_f32 v122, v197, 0x41900000, v69
	v_fmamk_f32 v123, v197, 0x41980000, v69
	v_fmamk_f32 v124, v197, 0x41c00000, v69
	v_fmamk_f32 v125, v197, 0x41c80000, v69
	v_fmamk_f32 v126, v197, 0x41d00000, v69
	v_fmamk_f32 v127, v197, 0x41d80000, v69
	v_fma_f32 v68, v200, v68, v174
	v_fmamk_f32 v96, v197, 0, v68
	v_fmamk_f32 v97, v197, 0x3f800000, v68
	v_fmamk_f32 v98, v197, 0x40000000, v68
	v_fmamk_f32 v99, v197, 0x40400000, v68
	v_fmamk_f32 v100, v197, 0x41000000, v68
	v_fmamk_f32 v101, v197, 0x41100000, v68
	v_fmamk_f32 v102, v197, 0x41200000, v68
	v_fmamk_f32 v103, v197, 0x41300000, v68
	v_fmamk_f32 v104, v197, 0x41800000, v68
	v_fmamk_f32 v105, v197, 0x41880000, v68
	v_fmamk_f32 v106, v197, 0x41900000, v68
	v_fmamk_f32 v107, v197, 0x41980000, v68
	v_fmamk_f32 v108, v197, 0x41c00000, v68
	v_fmamk_f32 v109, v197, 0x41c80000, v68
	v_fmamk_f32 v110, v197, 0x41d00000, v68
	v_fmamk_f32 v111, v197, 0x41d80000, v68
	s_add_i32 s4, s66, 0x8000
	s_waitcnt lgkmcnt(6)
	v_mfma_f32_32x32x16_bf16 v[96:111], v[64:67], v[140:143], v[96:111]
	s_add_i32 s67, s66, 0x4000
	s_add_i32 s66, s66, 0xc000
	v_cvt_f32_i32_e32 v64, v193
	s_waitcnt lgkmcnt(4)
	v_mfma_f32_32x32x16_bf16 v[96:111], v[74:77], v[136:139], v[96:111]
	s_waitcnt lgkmcnt(2)
	v_mfma_f32_32x32x16_bf16 v[96:111], v[78:81], v[132:135], v[96:111]
	s_waitcnt lgkmcnt(0)
	v_mfma_f32_32x32x16_bf16 v[96:111], v[82:85], v[128:131], v[96:111]
	v_mfma_f32_32x32x16_bf16 v[112:127], v[70:73], v[140:143], v[112:127]
	v_fma_f32 v65, v200, v64, v174
	v_add_f32_e32 v64, 0xc2000000, v64
	v_fma_f32 v79, v200, v64, v174
	v_fmamk_f32 v80, v197, 0, v65
	v_fmamk_f32 v81, v197, 0x3f800000, v65
	v_fmamk_f32 v82, v197, 0x40000000, v65
	v_fmamk_f32 v83, v197, 0x40400000, v65
	v_mfma_f32_32x32x16_bf16 v[112:127], v[214:217], v[136:139], v[112:127]
	v_fmamk_f32 v84, v197, 0x41000000, v65
	v_fmamk_f32 v85, v197, 0x41100000, v65
	v_fmamk_f32 v86, v197, 0x41200000, v65
	v_fmamk_f32 v87, v197, 0x41300000, v65
	v_fmamk_f32 v88, v197, 0x41800000, v65
	v_fmamk_f32 v89, v197, 0x41880000, v65
	v_fmamk_f32 v90, v197, 0x41900000, v65
	v_mfma_f32_32x32x16_bf16 v[112:127], v[218:221], v[132:135], v[112:127]
	v_add_u32_e32 v219, s67, v167
	v_fmamk_f32 v91, v197, 0x41980000, v65
	v_fmamk_f32 v92, v197, 0x41c00000, v65
	v_fmamk_f32 v93, v197, 0x41c80000, v65
	v_fmamk_f32 v94, v197, 0x41d00000, v65
	v_fmamk_f32 v95, v197, 0x41d80000, v65
	v_fmamk_f32 v64, v197, 0, v79
	v_fmamk_f32 v65, v197, 0x3f800000, v79
	v_fmamk_f32 v66, v197, 0x40000000, v79
	v_fmamk_f32 v67, v197, 0x40400000, v79
	v_fmamk_f32 v68, v197, 0x41000000, v79
	v_fmamk_f32 v69, v197, 0x41100000, v79
	v_fmamk_f32 v70, v197, 0x41200000, v79
	v_fmamk_f32 v71, v197, 0x41300000, v79
	v_fmamk_f32 v72, v197, 0x41800000, v79
	v_fmamk_f32 v73, v197, 0x41880000, v79
	v_fmamk_f32 v74, v197, 0x41900000, v79
	v_fmamk_f32 v75, v197, 0x41980000, v79
	v_fmamk_f32 v76, v197, 0x41c00000, v79
	v_fmamk_f32 v77, v197, 0x41c80000, v79
	v_fmamk_f32 v78, v197, 0x41d00000, v79
	v_fmamk_f32 v79, v197, 0x41d80000, v79
	ds_read_b128 v[226:229], v219
	ds_read_b128 v[230:233], v219 offset:8192
	v_add_u32_e32 v197, s4, v159
	v_add_u32_e32 v199, s4, v202
	v_add_u32_e32 v213, s4, v161
	v_add_u32_e32 v214, s4, v203
	v_add_u32_e32 v215, s4, v163
	v_add_u32_e32 v216, s4, v204
	v_add_u32_e32 v217, s4, v165
	v_add_u32_e32 v218, s4, v205
	v_mfma_f32_32x32x16_bf16 v[112:127], v[222:225], v[128:131], v[112:127]
	s_nop 11
	v_exp_f32_e32 v112, v112
	v_exp_f32_e32 v113, v113
	v_add_u32_e32 v219, s67, v169
	v_exp_f32_e32 v114, v114
	ds_read_b128 v[220:223], v219
	ds_read_b128 v[234:237], v219 offset:8192
	v_exp_f32_e32 v115, v115
	v_add_f32_e32 v195, v195, v112
	v_add_f32_e32 v195, v113, v195
	v_add_f32_e32 v195, v114, v195
	v_add_f32_e32 v195, v115, v195
	s_waitcnt lgkmcnt(3)
; #define ALDS __attribute__((address_space(3)))
; #define SBAR0() __builtin_amdgcn_sched_barrier(0)
; template <bool PAST, bool PAST1 = PAST>
; __device__ __forceinline__ void attn_pair(f32x16 (&o)[4], float& lsum, const bf16x8 (&qf)[4], const LaneAddr& A, unsigned k0, unsigned v0, unsigned k1, unsigned v1, float nslope2, float negM0, float dt0, float dt1) {
;     ...
; #pragma unroll
;     for (int g = 0; g < 8; ++g) {
;         const int ks = g >> 1, sub = g & 1;
;         if (sub == 0 && ks < 3) { const unsigned ka = A.kb[ks + 1] + k1; k2[(ks + 1) & 1][0] = *(const ALDS bf16x8*)(size_t)(ka); k2[(ks + 1) & 1][1] = *(const ALDS bf16x8*)(size_t)(ka + 8192u); }
;         MF32(s1[sub], k2[ks & 1][sub], qf[ks]);
; #pragma unroll
;         for (int k = 0; k < 4; ++k) { const int idx = 4 * g + k; s0[idx >> 4][idx & 15] = __builtin_amdgcn_exp2f(s0[idx >> 4][idx & 15]); lsum += s0[idx >> 4][idx & 15]; }
;         if (g & 1) pa0[g >> 2][(g >> 1) & 1] = pack8s(s0[g >> 2], 8 * ((g >> 1) & 1));
;         if (g == 6) {
; #pragma unroll
;             for (int et = 0; et < 4; ++et) { TR_ISSUE(vlo[0][et], va0[et][0], 0); TR_ISSUE(vhi[0][et], va0[et][1], 2048); } }
;         SBAR0();
;     }
;     tr_wait<4>(vlo[0], vhi[0]);
;     SBAR0();
;     unsigned va1[4][2];
; #pragma unroll
;     for (int g = 0; g < 16; ++g) {
;         const int step = g >> 2, et = g & 3, cur = step & 1, nxt = cur ^ 1;
;         if (et == 0) {
;             if (step < 3) {
; #pragma unroll
;                 for (int e2 = 0; e2 < 4; ++e2) { TR_ISSUE(vlo[nxt][e2], va0[e2][0], 256 * (32 * ((step + 1) >> 1) + 16 * ((step + 1) & 1))); TR_ISSUE(vhi[nxt][e2], va0[e2][1], 256 * (32 * ((step + 1) >> 1) + 16 * ((step + 1) & 1)) + 2048); }
;             } else {
; #pragma unroll
;                 for (int e2 = 0; e2 < 4; ++e2) { va1[e2][0] = A.vb[2 * e2] + v1; va1[e2][1] = A.vb[2 * e2 + 1] + v1; TR_ISSUE(vlo[nxt][e2], va1[e2][0], 0); TR_ISSUE(vhi[nxt][e2], va1[e2][1], 2048); }
;             }
;         }
;         MF32(o[et], VFRAG(cur, et), pa0[step >> 1][step & 1]);
; #pragma unroll
;         for (int k = 0; k < 2; ++k) { const int idx = 2 * g + k; s1[idx >> 4][idx & 15] = __builtin_amdgcn_exp2f(s1[idx >> 4][idx & 15]); lsum += s1[idx >> 4][idx & 15]; }
;         if (et == 3) { pa1[step >> 1][step & 1] = pack8s(s1[step >> 1], 8 * (step & 1)); tr_wait<4>(vlo[nxt], vhi[nxt]); }
;         SBAR0();
;     }
	v_mfma_f32_32x32x16_bf16 v[80:95], v[226:229], v[140:143], v[80:95]
	v_exp_f32_e32 v219, v116
	v_exp_f32_e32 v224, v118
	v_exp_f32_e32 v119, v119
	s_waitcnt lgkmcnt(2)
	v_mfma_f32_32x32x16_bf16 v[64:79], v[230:233], v[140:143], v[64:79]
	v_add_f32_e32 v116, v219, v195
	v_exp_f32_e32 v195, v117
	v_cvt_pk_bf16_f32 v117, v114, v115
	v_add_f32_e32 v116, v195, v116
	v_add_f32_e32 v116, v224, v116
	v_add_f32_e32 v232, v119, v116
	v_cvt_pk_bf16_f32 v116, v112, v113
	v_cvt_pk_bf16_f32 v118, v219, v195
	v_cvt_pk_bf16_f32 v119, v224, v119
	v_add_u32_e32 v112, s67, v171
	ds_read_b128 v[224:227], v112
	ds_read_b128 v[228:231], v112 offset:8192
	v_exp_f32_e32 v112, v120
	v_exp_f32_e32 v113, v121
	v_exp_f32_e32 v114, v122
	v_exp_f32_e32 v115, v123
	v_add_f32_e32 v120, v112, v232
	v_add_f32_e32 v120, v113, v120
	v_add_f32_e32 v120, v114, v120
	s_waitcnt lgkmcnt(3)
	v_mfma_f32_32x32x16_bf16 v[80:95], v[220:223], v[136:139], v[80:95]
	v_add_f32_e32 v120, v115, v120
	v_exp_f32_e32 v121, v124
	v_exp_f32_e32 v122, v125
	v_exp_f32_e32 v123, v126
	v_exp_f32_e32 v124, v127
	v_add_f32_e32 v120, v121, v120
	v_add_f32_e32 v120, v122, v120
	v_add_f32_e32 v120, v123, v120
	v_add_f32_e32 v195, v124, v120
	s_waitcnt lgkmcnt(2)
	v_mfma_f32_32x32x16_bf16 v[64:79], v[234:237], v[136:139], v[64:79]
	v_cvt_pk_bf16_f32 v112, v112, v113
	v_cvt_pk_bf16_f32 v113, v114, v115
	v_cvt_pk_bf16_f32 v114, v121, v122
	v_cvt_pk_bf16_f32 v115, v123, v124
	v_exp_f32_e32 v96, v96
	v_exp_f32_e32 v97, v97
	v_add_u32_e32 v124, s67, v173
	v_exp_f32_e32 v98, v98
	ds_read_b128 v[120:123], v124
	ds_read_b128 v[124:127], v124 offset:8192
	v_exp_f32_e32 v99, v99
	v_add_f32_e32 v195, v96, v195
	v_add_f32_e32 v195, v97, v195
	v_add_f32_e32 v195, v98, v195
	v_add_f32_e32 v195, v99, v195
	s_waitcnt lgkmcnt(3)
	v_mfma_f32_32x32x16_bf16 v[80:95], v[224:227], v[132:135], v[80:95]
	v_exp_f32_e32 v219, v100
	v_exp_f32_e32 v220, v102
	v_exp_f32_e32 v103, v103
	s_waitcnt lgkmcnt(2)
	v_mfma_f32_32x32x16_bf16 v[64:79], v[228:231], v[132:135], v[64:79]
	v_add_f32_e32 v100, v219, v195
	v_exp_f32_e32 v195, v101
	v_cvt_pk_bf16_f32 v101, v98, v99
	v_add_f32_e32 v100, v195, v100
	v_add_f32_e32 v100, v220, v100
	v_add_f32_e32 v221, v103, v100
	v_cvt_pk_bf16_f32 v100, v96, v97
	v_cvt_pk_bf16_f32 v102, v219, v195
	v_cvt_pk_bf16_f32 v103, v220, v103
	v_exp_f32_e32 v96, v104
	s_waitcnt lgkmcnt(1)
	v_mfma_f32_32x32x16_bf16 v[80:95], v[120:123], v[128:131], v[80:95]
	v_exp_f32_e32 v98, v105
	v_exp_f32_e32 v99, v106
	v_add_f32_e32 v97, v96, v221
	v_exp_f32_e32 v195, v107
	ds_read_b64_tr_b16 v[104:105], v197
	ds_read_b64_tr_b16 v[106:107], v199 offset:2048
	ds_read_b64_tr_b16 v[120:121], v213
	ds_read_b64_tr_b16 v[122:123], v214 offset:2048
	ds_read_b64_tr_b16 v[220:221], v215
	ds_read_b64_tr_b16 v[222:223], v216 offset:2048
	ds_read_b64_tr_b16 v[224:225], v217
	ds_read_b64_tr_b16 v[226:227], v218 offset:2048
	v_add_f32_e32 v97, v98, v97
	v_add_f32_e32 v97, v99, v97
	v_add_f32_e32 v97, v195, v97
	v_exp_f32_e32 v108, v108
	v_exp_f32_e32 v109, v109
	v_exp_f32_e32 v110, v110
	v_exp_f32_e32 v111, v111
	v_add_f32_e32 v97, v108, v97
	v_add_f32_e32 v97, v109, v97
	v_add_f32_e32 v97, v110, v97
	s_waitcnt lgkmcnt(8)
	v_mfma_f32_32x32x16_bf16 v[64:79], v[124:127], v[128:131], v[64:79]
	v_add_f32_e32 v219, v111, v97
	v_cvt_pk_bf16_f32 v96, v96, v98
	v_cvt_pk_bf16_f32 v97, v99, v195
	v_cvt_pk_bf16_f32 v98, v108, v109
	v_cvt_pk_bf16_f32 v99, v110, v111
	ds_read_b64_tr_b16 v[108:109], v197 offset:4096
	ds_read_b64_tr_b16 v[110:111], v199 offset:6144
	ds_read_b64_tr_b16 v[124:125], v213 offset:4096
	ds_read_b64_tr_b16 v[126:127], v214 offset:6144
	ds_read_b64_tr_b16 v[228:229], v215 offset:4096
	ds_read_b64_tr_b16 v[230:231], v216 offset:6144
	ds_read_b64_tr_b16 v[232:233], v217 offset:4096
	ds_read_b64_tr_b16 v[234:235], v218 offset:6144
	s_waitcnt lgkmcnt(14)
	v_mfma_f32_32x32x16_bf16 v[48:63], v[104:107], v[116:119], v[48:63]
	v_exp_f32_e32 v80, v80
	v_exp_f32_e32 v81, v81
	v_add_f32_e32 v104, v80, v219
	v_add_f32_e32 v104, v81, v104
	s_waitcnt lgkmcnt(12)
	v_mfma_f32_32x32x16_bf16 v[32:47], v[120:123], v[116:119], v[32:47]
	v_exp_f32_e32 v82, v82
	v_exp_f32_e32 v83, v83
	v_add_f32_e32 v104, v82, v104
	v_add_f32_e32 v104, v83, v104
	s_waitcnt lgkmcnt(10)
	v_mfma_f32_32x32x16_bf16 v[16:31], v[220:223], v[116:119], v[16:31]
	v_exp_f32_e32 v84, v84
	v_exp_f32_e32 v85, v85
	v_add_f32_e32 v104, v84, v104
	v_add_f32_e32 v104, v85, v104
	s_waitcnt lgkmcnt(8)
	v_mfma_f32_32x32x16_bf16 v[0:15], v[224:227], v[116:119], v[0:15]
	v_exp_f32_e32 v86, v86
	v_exp_f32_e32 v87, v87
	v_cvt_pk_bf16_f32 v80, v80, v81
	v_cvt_pk_bf16_f32 v81, v82, v83
	v_add_f32_e32 v104, v86, v104
	v_add_f32_e32 v195, v87, v104
	v_cvt_pk_bf16_f32 v82, v84, v85
	v_cvt_pk_bf16_f32 v83, v86, v87
	ds_read_b64_tr_b16 v[104:105], v197 offset:8192
	ds_read_b64_tr_b16 v[106:107], v199 offset:10240
	ds_read_b64_tr_b16 v[116:117], v213 offset:8192
	ds_read_b64_tr_b16 v[118:119], v214 offset:10240
	ds_read_b64_tr_b16 v[120:121], v215 offset:8192
	ds_read_b64_tr_b16 v[122:123], v216 offset:10240
	ds_read_b64_tr_b16 v[220:221], v217 offset:8192
	ds_read_b64_tr_b16 v[222:223], v218 offset:10240
	s_waitcnt lgkmcnt(14)
	v_mfma_f32_32x32x16_bf16 v[48:63], v[108:111], v[112:115], v[48:63]
	v_exp_f32_e32 v84, v88
	v_exp_f32_e32 v86, v89
	v_add_f32_e32 v85, v84, v195
	v_add_f32_e32 v85, v86, v85
	s_waitcnt lgkmcnt(12)
	v_mfma_f32_32x32x16_bf16 v[32:47], v[124:127], v[112:115], v[32:47]
	v_exp_f32_e32 v87, v90
	v_exp_f32_e32 v88, v91
	v_add_f32_e32 v85, v87, v85
	v_add_f32_e32 v85, v88, v85
	s_waitcnt lgkmcnt(10)
; template <bool PAST, bool PAST1 = PAST>
; __device__ __forceinline__ void attn_pair(f32x16 (&o)[4], float& lsum, const bf16x8 (&qf)[4], const LaneAddr& A, unsigned k0, unsigned v0, unsigned k1, unsigned v1, float nslope2, float negM0, float dt0, float dt1) {
;     ...
;     unsigned va1[4][2];
; #pragma unroll
;     for (int g = 0; g < 16; ++g) {
;         const int step = g >> 2, et = g & 3, cur = step & 1, nxt = cur ^ 1;
;         if (et == 0) {
;             if (step < 3) {
; #pragma unroll
;                 for (int e2 = 0; e2 < 4; ++e2) { TR_ISSUE(vlo[nxt][e2], va0[e2][0], 256 * (32 * ((step + 1) >> 1) + 16 * ((step + 1) & 1))); TR_ISSUE(vhi[nxt][e2], va0[e2][1], 256 * (32 * ((step + 1) >> 1) + 16 * ((step + 1) & 1)) + 2048); }
;             } else {
; #pragma unroll
;                 for (int e2 = 0; e2 < 4; ++e2) { va1[e2][0] = A.vb[2 * e2] + v1; va1[e2][1] = A.vb[2 * e2 + 1] + v1; TR_ISSUE(vlo[nxt][e2], va1[e2][0], 0); TR_ISSUE(vhi[nxt][e2], va1[e2][1], 2048); }
;             }
;         }
;         MF32(o[et], VFRAG(cur, et), pa0[step >> 1][step & 1]);
; #pragma unroll
;         for (int k = 0; k < 2; ++k) { const int idx = 2 * g + k; s1[idx >> 4][idx & 15] = __builtin_amdgcn_exp2f(s1[idx >> 4][idx & 15]); lsum += s1[idx >> 4][idx & 15]; }
;         if (et == 3) { pa1[step >> 1][step & 1] = pack8s(s1[step >> 1], 8 * (step & 1)); tr_wait<4>(vlo[nxt], vhi[nxt]); }
;         SBAR0();
;     }
;     if (PROBE == 7) { float dmy = negM0;
; #pragma unroll
;         for (int i = 0; i < 64; ++i) asm volatile("v_exp_f32 %0, %0" : "+v"(dmy)); }
;     if (PROBE == 8) { s16x4 dm;
; #pragma unroll
;         for (int i = 0; i < 64; ++i) asm volatile("ds_read_b64_tr_b16 %0, %1 offset:%c2" : "=&v"(dm) : "v"(va1[i & 3][0]), "i"((i >> 2) * 512) : "memory");
;         asm volatile("s_waitcnt lgkmcnt(0)" ::: "memory"); }
; #pragma unroll
;     for (int step = 0; step < 4; ++step) {
;         const int cur = step & 1, nxt = cur ^ 1;
;         if (step < 3) {
; #pragma unroll
;             for (int e2 = 0; e2 < 4; ++e2) { TR_ISSUE(vlo[nxt][e2], va1[e2][0], 256 * (32 * ((step + 1) >> 1) + 16 * ((step + 1) & 1))); TR_ISSUE(vhi[nxt][e2], va1[e2][1], 256 * (32 * ((step + 1) >> 1) + 16 * ((step + 1) & 1)) + 2048); } }
; #pragma unroll
;         for (int et = 0; et < 4; ++et) MF32(o[et], VFRAG(cur, et), pa1[step >> 1][step & 1]);
;         if (step < 3) tr_wait<4>(vlo[nxt], vhi[nxt]);
	v_mfma_f32_32x32x16_bf16 v[16:31], v[228:231], v[112:115], v[16:31]
	v_exp_f32_e32 v89, v92
	v_exp_f32_e32 v90, v93
	v_add_f32_e32 v85, v89, v85
	v_add_f32_e32 v85, v90, v85
	s_waitcnt lgkmcnt(8)
	v_mfma_f32_32x32x16_bf16 v[0:15], v[232:235], v[112:115], v[0:15]
	v_exp_f32_e32 v91, v94
	v_exp_f32_e32 v92, v95
	v_cvt_pk_bf16_f32 v84, v84, v86
	v_cvt_pk_bf16_f32 v86, v89, v90
	v_add_f32_e32 v85, v91, v85
	v_add_f32_e32 v124, v92, v85
	v_cvt_pk_bf16_f32 v85, v87, v88
	v_cvt_pk_bf16_f32 v87, v91, v92
	ds_read_b64_tr_b16 v[88:89], v197 offset:12288
	ds_read_b64_tr_b16 v[90:91], v199 offset:14336
	ds_read_b64_tr_b16 v[92:93], v213 offset:12288
	ds_read_b64_tr_b16 v[94:95], v214 offset:14336
	ds_read_b64_tr_b16 v[108:109], v215 offset:12288
	ds_read_b64_tr_b16 v[110:111], v216 offset:14336
	ds_read_b64_tr_b16 v[112:113], v217 offset:12288
	ds_read_b64_tr_b16 v[114:115], v218 offset:14336
	s_waitcnt lgkmcnt(14)
	v_mfma_f32_32x32x16_bf16 v[48:63], v[104:107], v[100:103], v[48:63]
	v_exp_f32_e32 v64, v64
	v_exp_f32_e32 v65, v65
	v_add_f32_e32 v104, v64, v124
	v_add_f32_e32 v104, v65, v104
	s_waitcnt lgkmcnt(12)
	v_mfma_f32_32x32x16_bf16 v[32:47], v[116:119], v[100:103], v[32:47]
	v_exp_f32_e32 v66, v66
	v_exp_f32_e32 v67, v67
	v_add_f32_e32 v104, v66, v104
	v_add_f32_e32 v104, v67, v104
	s_waitcnt lgkmcnt(10)
	v_mfma_f32_32x32x16_bf16 v[16:31], v[120:123], v[100:103], v[16:31]
	v_exp_f32_e32 v68, v68
	v_exp_f32_e32 v69, v69
	v_add_f32_e32 v104, v68, v104
	v_add_f32_e32 v104, v69, v104
	s_waitcnt lgkmcnt(8)
	v_mfma_f32_32x32x16_bf16 v[0:15], v[220:223], v[100:103], v[0:15]
	v_exp_f32_e32 v70, v70
	v_exp_f32_e32 v71, v71
	v_cvt_pk_bf16_f32 v64, v64, v65
	v_cvt_pk_bf16_f32 v65, v66, v67
	v_add_f32_e32 v100, v70, v104
	v_add_f32_e32 v120, v71, v100
	v_cvt_pk_bf16_f32 v66, v68, v69
	v_cvt_pk_bf16_f32 v67, v70, v71
	s_waitcnt lgkmcnt(6)
	v_mfma_f32_32x32x16_bf16 v[48:63], v[88:91], v[96:99], v[48:63]
	v_exp_f32_e32 v199, v72
	v_add_u32_e32 v121, s66, v159
	v_add_u32_e32 v123, s66, v161
	v_add_u32_e32 v125, s66, v163
	v_add_u32_e32 v127, s66, v165
	v_add_u32_e32 v122, s66, v202
	ds_read_b64_tr_b16 v[68:69], v121
	ds_read_b64_tr_b16 v[70:71], v122 offset:2048
	v_add_u32_e32 v124, s66, v203
	ds_read_b64_tr_b16 v[100:101], v123
	ds_read_b64_tr_b16 v[102:103], v124 offset:2048
	v_add_u32_e32 v126, s66, v204
	ds_read_b64_tr_b16 v[104:105], v125
	ds_read_b64_tr_b16 v[106:107], v126 offset:2048
	v_add_u32_e32 v197, s66, v205
	ds_read_b64_tr_b16 v[116:117], v127
	ds_read_b64_tr_b16 v[118:119], v197 offset:2048
	v_add_f32_e32 v72, v199, v120
	v_exp_f32_e32 v120, v73
	s_nop 0
	v_add_f32_e32 v72, v120, v72
	s_waitcnt lgkmcnt(12)
	v_mfma_f32_32x32x16_bf16 v[32:47], v[92:95], v[96:99], v[32:47]
	v_exp_f32_e32 v92, v74
	v_exp_f32_e32 v93, v75
	v_add_f32_e32 v72, v92, v72
	v_add_f32_e32 v72, v93, v72
	s_waitcnt lgkmcnt(10)
	v_mfma_f32_32x32x16_bf16 v[16:31], v[108:111], v[96:99], v[16:31]
	v_exp_f32_e32 v94, v76
	v_exp_f32_e32 v95, v77
	v_add_f32_e32 v72, v94, v72
	v_add_f32_e32 v72, v95, v72
	s_waitcnt lgkmcnt(8)
	v_mfma_f32_32x32x16_bf16 v[0:15], v[112:115], v[96:99], v[0:15]
	v_exp_f32_e32 v96, v78
	v_exp_f32_e32 v97, v79
	v_add_f32_e32 v72, v96, v72
	v_add_f32_e32 v195, v97, v72
	s_waitcnt lgkmcnt(6)
	v_mfma_f32_32x32x16_bf16 v[48:63], v[68:71], v[80:83], v[48:63]
	ds_read_b64_tr_b16 v[68:69], v121 offset:4096
	ds_read_b64_tr_b16 v[70:71], v122 offset:6144
	ds_read_b64_tr_b16 v[72:73], v123 offset:4096
	ds_read_b64_tr_b16 v[74:75], v124 offset:6144
	ds_read_b64_tr_b16 v[76:77], v125 offset:4096
	ds_read_b64_tr_b16 v[78:79], v126 offset:6144
	ds_read_b64_tr_b16 v[88:89], v127 offset:4096
	ds_read_b64_tr_b16 v[90:91], v197 offset:6144
	s_waitcnt lgkmcnt(12)
	v_mfma_f32_32x32x16_bf16 v[32:47], v[100:103], v[80:83], v[32:47]
	s_waitcnt lgkmcnt(10)
	v_mfma_f32_32x32x16_bf16 v[16:31], v[104:107], v[80:83], v[16:31]
	s_waitcnt lgkmcnt(8)
	v_mfma_f32_32x32x16_bf16 v[0:15], v[116:119], v[80:83], v[0:15]
	s_waitcnt lgkmcnt(6)
	v_mfma_f32_32x32x16_bf16 v[48:63], v[68:71], v[84:87], v[48:63]
	ds_read_b64_tr_b16 v[68:69], v121 offset:8192
	s_waitcnt lgkmcnt(5)
	v_mfma_f32_32x32x16_bf16 v[32:47], v[72:75], v[84:87], v[32:47]
	s_waitcnt lgkmcnt(3)
	v_mfma_f32_32x32x16_bf16 v[16:31], v[76:79], v[84:87], v[16:31]
	ds_read_b64_tr_b16 v[70:71], v122 offset:10240
	ds_read_b64_tr_b16 v[72:73], v123 offset:8192
	ds_read_b64_tr_b16 v[74:75], v124 offset:10240
	ds_read_b64_tr_b16 v[76:77], v125 offset:8192
	ds_read_b64_tr_b16 v[78:79], v126 offset:10240
	ds_read_b64_tr_b16 v[80:81], v127 offset:8192
	ds_read_b64_tr_b16 v[82:83], v197 offset:10240
	s_waitcnt lgkmcnt(8)
	v_mfma_f32_32x32x16_bf16 v[0:15], v[88:91], v[84:87], v[0:15]
	s_waitcnt lgkmcnt(6)
	v_mfma_f32_32x32x16_bf16 v[48:63], v[68:71], v[64:67], v[48:63]
	ds_read_b64_tr_b16 v[68:69], v121 offset:12288
	s_waitcnt lgkmcnt(5)
	v_mfma_f32_32x32x16_bf16 v[32:47], v[72:75], v[64:67], v[32:47]
	s_waitcnt lgkmcnt(3)
	v_mfma_f32_32x32x16_bf16 v[16:31], v[76:79], v[64:67], v[16:31]
	ds_read_b64_tr_b16 v[70:71], v122 offset:14336
	ds_read_b64_tr_b16 v[72:73], v123 offset:12288
	ds_read_b64_tr_b16 v[74:75], v124 offset:14336
	ds_read_b64_tr_b16 v[76:77], v125 offset:12288
	ds_read_b64_tr_b16 v[78:79], v126 offset:14336
	ds_read_b64_tr_b16 v[84:85], v127 offset:12288
	ds_read_b64_tr_b16 v[86:87], v197 offset:14336
	s_waitcnt lgkmcnt(8)
	v_mfma_f32_32x32x16_bf16 v[0:15], v[80:83], v[64:67], v[0:15]
	v_cvt_pk_bf16_f32 v64, v199, v120
	v_cvt_pk_bf16_f32 v65, v92, v93
	v_cvt_pk_bf16_f32 v66, v94, v95
	v_cvt_pk_bf16_f32 v67, v96, v97
	s_waitcnt lgkmcnt(6)
	s_nop 0
	v_mfma_f32_32x32x16_bf16 v[48:63], v[68:71], v[64:67], v[48:63]
	s_waitcnt lgkmcnt(4)
	v_mfma_f32_32x32x16_bf16 v[32:47], v[72:75], v[64:67], v[32:47]
	s_waitcnt lgkmcnt(2)
	v_mfma_f32_32x32x16_bf16 v[16:31], v[76:79], v[64:67], v[16:31]
	s_waitcnt lgkmcnt(0)
	v_mfma_f32_32x32x16_bf16 v[0:15], v[84:87], v[64:67], v[0:15]
	s_waitcnt vmcnt(0) lgkmcnt(0)
	s_barrier
	s_add_i32 s65, s65, -1
	s_add_i32 s22, s22, 0x10000
	s_addk_i32 s64, 0x80
	s_cmp_eq_u32 s65, 0
	v_add_u32_e32 v193, 0xffffff80, v193
	s_cbranch_scc0 .LBB0_1853
